# store lane permutation (quad-contiguous 64 B per row) on P1, P3 and P8 epilogues
# baseline (speedup 1.0000x reference)
; __device__ __forceinline__ unsigned cvt_pk_bf16(float lo, float hi) { unsigned r; asm volatile("v_cvt_pk_bf16_f32 %0, %1, %2" : "=v"(r) : "v"(lo), "v"(hi)); return r; }
;     __device__ __forceinline__ void operator()(const f32x4 (&acc)[2][2][4][2], const Unit& u, int wr, int wc, int fr, int fq) const {
;         const int row0 = u.pm * BM + wr * 64 + fr, col0 = u.pn * HALF + wc * 32 + 8 * fq;
;         unsigned long long sq[2][4];
; #pragma unroll
;         for (int ai = 0; ai < 2; ++ai)
; #pragma unroll
;             for (int m = 0; m < 4; ++m) sq[ai][m] = ssq[row0 + ai * HALF + m * 16];
; #pragma unroll
;         for (int ai = 0; ai < 2; ++ai)
; #pragma unroll
;             for (int m = 0; m < 4; ++m) {
;                 const int row = row0 + ai * HALF + m * 16; const float rs = rsqrtf((float)sq[ai][m] * (1.0f / FIXS) * (1.0f / (float)D) + EPS);
;                 typedef float f2 __attribute__((ext_vector_type(2)));
;                 const float c1 = -1.4426950408889634f * rs, c2 = rs * rs;
;                 u32x4 w; unsigned wq[4];
; #pragma unroll
;                 for (int q = 0; q < 4; ++q) { const f32x4 gg = acc[ai][0][m][q >> 1], uu = acc[ai][1][m][q >> 1];
;                     const f2 g = {gg[2 * (q & 1)], gg[2 * (q & 1) + 1]}, u2 = {uu[2 * (q & 1)], uu[2 * (q & 1) + 1]};
;                     const f2 t = g * c1; const f2 e = {__builtin_amdgcn_exp2f(t.x), __builtin_amdgcn_exp2f(t.y)};
;                     const f2 d = e + 1.0f; const f2 r = {__builtin_amdgcn_rcpf(d.x), __builtin_amdgcn_rcpf(d.y)};
;                     const f2 o = (g * u2) * (r * c2);
;                     wq[q] = cvt_pk_bf16(o.x, o.y); }
;                 w.x = wq[0]; w.y = wq[1]; w.z = wq[2]; w.w = wq[3];
;                 *(u32x4*)(O + (size_t)row * LDF + col0) = w;
;             }
;     }
.LBB0_236:
	v_mbcnt_lo_u32_b32 v233, -1, 0
	v_mbcnt_hi_u32_b32 v233, -1, v233
	v_lshrrev_b32_e32 v232, 2, v233
	v_and_b32_e32 v233, 3, v233
	v_lshl_add_u32 v232, v233, 4, v232
	v_lshlrev_b32_e32 v232, 2, v232
	v_lshl_add_u32 v144, s20, 8, v152
	v_ashrrev_i32_e32 v145, 31, v144
	v_lshl_add_u64 v[162:163], v[144:145], 3, s[6:7]
	v_or_b32_e32 v146, 16, v144
	global_load_dwordx2 v[164:165], v[162:163], off
	v_ashrrev_i32_e32 v147, 31, v146
	v_lshl_add_u64 v[148:149], v[146:147], 3, s[6:7]
	global_load_dwordx2 v[166:167], v[148:149], off
	v_lshl_add_u32 v150, s21, 7, v154
	v_pk_mul_f32 v[168:169], v[114:115], v[126:127]
	v_or_b32_e32 v148, 32, v144
	v_or_b32_e32 v126, 48, v144
	v_ashrrev_i32_e32 v151, 31, v150
	v_ashrrev_i32_e32 v149, 31, v148
	v_ashrrev_i32_e32 v127, 31, v126
	v_pk_mul_f32 v[174:175], v[108:109], v[120:121]
	v_mov_b64_e32 v[120:121], s[30:31]
	v_pk_mul_f32 v[176:177], v[106:107], v[118:119]
	v_pk_mul_f32 v[178:179], v[104:105], v[116:117]
	v_lshlrev_b64 v[116:117], 1, v[150:151]
	v_lshl_add_u64 v[118:119], v[148:149], 3, s[6:7]
	v_lshl_add_u64 v[150:151], v[126:127], 3, s[6:7]
	v_pk_mul_f32 v[170:171], v[112:113], v[124:125]
	v_pk_mul_f32 v[172:173], v[110:111], v[122:123]
	v_add_u32_e32 v161, 0x80, v144
	v_add_u32_e32 v160, 0x90, v144
	v_add_u32_e32 v159, 0xa0, v144
	v_add_u32_e32 v147, 0xb0, v144
	v_mad_i64_i32 v[180:181], s[4:5], v144, s61, v[120:121]
	global_load_dwordx2 v[144:145], v[162:163], off offset:1024
	global_load_dwordx2 v[124:125], v[162:163], off offset:1152
	global_load_dwordx2 v[122:123], v[162:163], off offset:1280
	global_load_dwordx2 v[182:183], v[118:119], off
	s_nop 0
	global_load_dwordx2 v[150:151], v[150:151], off
	s_nop 0
	global_load_dwordx2 v[118:119], v[162:163], off offset:1408
	v_pk_mul_f32 v[96:97], v[100:101], v[96:97]
	v_pk_mul_f32 v[98:99], v[102:103], v[98:99]
	v_pk_mul_f32 v[88:89], v[92:93], v[88:89]
	v_pk_mul_f32 v[90:91], v[94:95], v[90:91]
	v_pk_mul_f32 v[80:81], v[84:85], v[80:81]
	v_pk_mul_f32 v[82:83], v[86:87], v[82:83]
	v_pk_mul_f32 v[72:73], v[76:77], v[72:73]
	v_pk_mul_f32 v[74:75], v[78:79], v[74:75]
	v_pk_mul_f32 v[64:65], v[68:69], v[64:65]
	v_pk_mul_f32 v[66:67], v[70:71], v[66:67]
	v_pk_mul_f32 v[56:57], v[60:61], v[56:57]
	v_pk_mul_f32 v[58:59], v[62:63], v[58:59]
	v_pk_mul_f32 v[48:49], v[52:53], v[48:49]
	v_pk_mul_f32 v[50:51], v[54:55], v[50:51]
	v_pk_mul_f32 v[40:41], v[44:45], v[40:41]
	v_pk_mul_f32 v[42:43], v[46:47], v[42:43]
	v_pk_mul_f32 v[32:33], v[36:37], v[32:33]
	v_pk_mul_f32 v[34:35], v[38:39], v[34:35]
	v_pk_mul_f32 v[24:25], v[28:29], v[24:25]
	v_pk_mul_f32 v[26:27], v[30:31], v[26:27]
	v_pk_mul_f32 v[16:17], v[20:21], v[16:17]
	v_pk_mul_f32 v[18:19], v[22:23], v[18:19]
	v_pk_mul_f32 v[8:9], v[12:13], v[8:9]
	v_pk_mul_f32 v[10:11], v[14:15], v[10:11]
	v_pk_mul_f32 v[0:1], v[4:5], v[0:1]
	v_pk_mul_f32 v[2:3], v[6:7], v[2:3]
	s_waitcnt vmcnt(0)
	v_ffbh_u32_e32 v127, v165
	v_min_u32_e32 v127, 32, v127
	v_lshlrev_b64 v[162:163], v127, v[164:165]
	v_ffbh_u32_e32 v149, v167
	v_min_u32_e32 v149, 32, v149
	v_min_u32_e32 v162, 1, v162
	v_lshlrev_b64 v[164:165], v149, v[166:167]
	v_or_b32_e32 v162, v163, v162
	v_min_u32_e32 v163, 1, v164
	v_cvt_f32_u32_e32 v162, v162
	v_or_b32_e32 v163, v165, v163
	v_cvt_f32_u32_e32 v163, v163
	v_sub_u32_e32 v127, 32, v127
	v_ldexp_f32 v127, v162, v127
	v_sub_u32_e32 v149, 32, v149
	v_mul_f32_e32 v127, 0x33800000, v127
	v_ldexp_f32 v149, v163, v149
	v_fmamk_f32 v127, v127, 0x39800000, v158
	v_mul_f32_e32 v149, 0x33800000, v149
	v_mul_f32_e32 v162, 0x4b800000, v127
	v_cmp_gt_f32_e32 vcc, s60, v127
	v_fmamk_f32 v149, v149, 0x39800000, v158
	v_cmp_gt_f32_e64 s[4:5], s60, v149
	v_cndmask_b32_e32 v127, v127, v162, vcc
	v_mul_f32_e32 v162, 0x4b800000, v149
	v_rsq_f32_e32 v127, v127
	v_cndmask_b32_e64 v149, v149, v162, s[4:5]
	v_rsq_f32_e32 v149, v149
	v_lshl_add_u64 v[162:163], v[180:181], 0, v[116:117]
	v_mul_f32_e32 v164, 0x45800000, v127
	v_cndmask_b32_e32 v127, v127, v164, vcc
	v_mul_f32_e32 v165, 0x45800000, v149
	v_mul_f32_e32 v164, 0xbfb8aa3b, v127
	v_pk_mul_f32 v[112:113], v[112:113], v[164:165] op_sel_hi:[1,0]
	v_pk_mul_f32 v[114:115], v[114:115], v[164:165] op_sel_hi:[1,0]
	v_pk_mul_f32 v[108:109], v[108:109], v[164:165] op_sel_hi:[1,0]
	v_pk_mul_f32 v[110:111], v[110:111], v[164:165] op_sel_hi:[1,0]
	v_exp_f32_e32 v112, v112
	v_exp_f32_e32 v113, v113
	v_exp_f32_e32 v114, v114
	v_exp_f32_e32 v115, v115
	v_mul_f32_e32 v166, v127, v127
	v_cndmask_b32_e64 v127, v149, v165, s[4:5]
	v_exp_f32_e32 v108, v108
	v_exp_f32_e32 v109, v109
	v_exp_f32_e32 v110, v110
	v_exp_f32_e32 v111, v111
	v_mul_f32_e32 v164, 0xbfb8aa3b, v127
	v_pk_mul_f32 v[104:105], v[104:105], v[164:165] op_sel_hi:[1,0]
	v_pk_mul_f32 v[184:185], v[106:107], v[164:165] op_sel_hi:[1,0]
	v_exp_f32_e32 v104, v104
	v_exp_f32_e32 v105, v105
	v_pk_add_f32 v[106:107], v[112:113], 1.0 op_sel_hi:[1,0]
	v_pk_add_f32 v[112:113], v[114:115], 1.0 op_sel_hi:[1,0]
	v_pk_add_f32 v[108:109], v[108:109], 1.0 op_sel_hi:[1,0]
	v_pk_add_f32 v[110:111], v[110:111], 1.0 op_sel_hi:[1,0]
	v_rcp_f32_e32 v106, v106
	v_rcp_f32_e32 v107, v107
	v_rcp_f32_e32 v112, v112
	v_rcp_f32_e32 v113, v113
	v_rcp_f32_e32 v108, v108
	v_rcp_f32_e32 v109, v109
	v_rcp_f32_e32 v110, v110
	v_rcp_f32_e32 v111, v111
	v_exp_f32_e32 v184, v184
	v_pk_add_f32 v[104:105], v[104:105], 1.0 op_sel_hi:[1,0]
	v_exp_f32_e32 v185, v185
	v_rcp_f32_e32 v114, v104
	v_rcp_f32_e32 v115, v105
	v_pk_mul_f32 v[104:105], v[166:167], v[106:107] op_sel_hi:[0,1]
	v_pk_mul_f32 v[106:107], v[166:167], v[112:113] op_sel_hi:[0,1]
	v_pk_mul_f32 v[108:109], v[166:167], v[108:109] op_sel_hi:[0,1]
	v_pk_mul_f32 v[110:111], v[166:167], v[110:111] op_sel_hi:[0,1]
	v_pk_mul_f32 v[104:105], v[170:171], v[104:105]
	v_pk_mul_f32 v[106:107], v[168:169], v[106:107]
	v_pk_mul_f32 v[108:109], v[174:175], v[108:109]
	v_pk_mul_f32 v[110:111], v[172:173], v[110:111]
	v_cvt_pk_bf16_f32 v104, v104, v105
	v_cvt_pk_bf16_f32 v105, v106, v107
	v_cvt_pk_bf16_f32 v106, v108, v109
	v_pk_mul_f32 v[108:109], v[100:101], v[164:165] op_sel_hi:[1,0]
	v_cvt_pk_bf16_f32 v107, v110, v111
	ds_bpermute_b32 v230, v232, v162
	ds_bpermute_b32 v231, v232, v163
	ds_bpermute_b32 v226, v232, v104
	ds_bpermute_b32 v227, v232, v105
	ds_bpermute_b32 v228, v232, v106
	ds_bpermute_b32 v229, v232, v107
	s_waitcnt lgkmcnt(0)
; __device__ __forceinline__ unsigned cvt_pk_bf16(float lo, float hi) { unsigned r; asm volatile("v_cvt_pk_bf16_f32 %0, %1, %2" : "=v"(r) : "v"(lo), "v"(hi)); return r; }
;     __device__ __forceinline__ void operator()(const f32x4 (&acc)[2][2][4][2], const Unit& u, int wr, int wc, int fr, int fq) const {
;     ...
;             for (int m = 0; m < 4; ++m) {
;                 const int row = row0 + ai * HALF + m * 16; const float rs = rsqrtf((float)sq[ai][m] * (1.0f / FIXS) * (1.0f / (float)D) + EPS);
;                 typedef float f2 __attribute__((ext_vector_type(2)));
;                 const float c1 = -1.4426950408889634f * rs, c2 = rs * rs;
;                 u32x4 w; unsigned wq[4];
; #pragma unroll
;                 for (int q = 0; q < 4; ++q) { const f32x4 gg = acc[ai][0][m][q >> 1], uu = acc[ai][1][m][q >> 1];
;                     const f2 g = {gg[2 * (q & 1)], gg[2 * (q & 1) + 1]}, u2 = {uu[2 * (q & 1)], uu[2 * (q & 1) + 1]};
;                     const f2 t = g * c1; const f2 e = {__builtin_amdgcn_exp2f(t.x), __builtin_amdgcn_exp2f(t.y)};
;                     const f2 d = e + 1.0f; const f2 r = {__builtin_amdgcn_rcpf(d.x), __builtin_amdgcn_rcpf(d.y)};
;                     const f2 o = (g * u2) * (r * c2);
;                     wq[q] = cvt_pk_bf16(o.x, o.y); }
;                 w.x = wq[0]; w.y = wq[1]; w.z = wq[2]; w.w = wq[3];
;                 *(u32x4*)(O + (size_t)row * LDF + col0) = w;
;             }
	global_store_dwordx4 v[230:231], v[226:229], off
	v_exp_f32_e32 v108, v108
	v_exp_f32_e32 v109, v109
	v_pk_add_f32 v[106:107], v[184:185], 1.0 op_sel_hi:[1,0]
	v_mul_f32_e32 v180, v127, v127
	v_rcp_f32_e32 v106, v106
	v_rcp_f32_e32 v107, v107
	v_pk_mul_f32 v[104:105], v[180:181], v[114:115] op_sel_hi:[0,1]
	v_pk_mul_f32 v[104:105], v[178:179], v[104:105]
	v_pk_mul_f32 v[100:101], v[102:103], v[164:165] op_sel_hi:[1,0]
	v_pk_mul_f32 v[106:107], v[180:181], v[106:107] op_sel_hi:[0,1]
	v_pk_mul_f32 v[106:107], v[176:177], v[106:107]
	v_cvt_pk_bf16_f32 v104, v104, v105
	v_exp_f32_e32 v100, v100
	v_cvt_pk_bf16_f32 v105, v106, v107
	v_pk_add_f32 v[106:107], v[108:109], 1.0 op_sel_hi:[1,0]
	v_exp_f32_e32 v101, v101
	v_rcp_f32_e32 v106, v106
	v_rcp_f32_e32 v107, v107
	s_nop 0
	v_pk_mul_f32 v[102:103], v[180:181], v[106:107] op_sel_hi:[0,1]
	v_pk_mul_f32 v[96:97], v[96:97], v[102:103]
	s_nop 0
	v_cvt_pk_bf16_f32 v106, v96, v97
	v_pk_add_f32 v[96:97], v[100:101], 1.0 op_sel_hi:[1,0]
	v_ffbh_u32_e32 v100, v183
	v_min_u32_e32 v102, 32, v100
	v_lshlrev_b64 v[100:101], v102, v[182:183]
	v_rcp_f32_e32 v96, v96
	v_rcp_f32_e32 v97, v97
	v_min_u32_e32 v100, 1, v100
	v_or_b32_e32 v100, v101, v100
	v_cvt_f32_u32_e32 v100, v100
	v_pk_mul_f32 v[96:97], v[180:181], v[96:97] op_sel_hi:[0,1]
	v_pk_mul_f32 v[96:97], v[98:99], v[96:97]
	v_sub_u32_e32 v98, 32, v102
	v_ldexp_f32 v98, v100, v98
	v_mul_f32_e32 v98, 0x33800000, v98
	v_fmamk_f32 v98, v98, 0x39800000, v158
	v_mul_f32_e32 v99, 0x4b800000, v98
	v_cmp_gt_f32_e32 vcc, s60, v98
	v_cvt_pk_bf16_f32 v107, v96, v97
	v_mad_i64_i32 v[96:97], s[4:5], v146, s61, v[120:121]
	s_nop 0
	v_cndmask_b32_e32 v98, v98, v99, vcc
	v_rsq_f32_e32 v98, v98
	v_lshl_add_u64 v[96:97], v[96:97], 0, v[116:117]
	ds_bpermute_b32 v230, v232, v96
	ds_bpermute_b32 v231, v232, v97
	ds_bpermute_b32 v234, v232, v104
	ds_bpermute_b32 v235, v232, v105
	ds_bpermute_b32 v236, v232, v106
	ds_bpermute_b32 v237, v232, v107
	s_waitcnt lgkmcnt(0)
	global_store_dwordx4 v[230:231], v[234:237], off
	v_mul_f32_e32 v99, 0x45800000, v98
	v_cndmask_b32_e32 v99, v98, v99, vcc
	v_mul_f32_e32 v98, 0xbfb8aa3b, v99
	v_pk_mul_f32 v[100:101], v[92:93], v[98:99] op_sel_hi:[1,0]
	v_pk_mul_f32 v[92:93], v[94:95], v[98:99] op_sel_hi:[1,0]
	v_exp_f32_e32 v100, v100
	v_exp_f32_e32 v101, v101
	v_exp_f32_e32 v92, v92
	v_exp_f32_e32 v93, v93
	v_mul_f32_e32 v96, v99, v99
	v_pk_add_f32 v[100:101], v[100:101], 1.0 op_sel_hi:[1,0]
	v_pk_add_f32 v[92:93], v[92:93], 1.0 op_sel_hi:[1,0]
	v_rcp_f32_e32 v100, v100
	v_rcp_f32_e32 v101, v101
	v_rcp_f32_e32 v92, v92
	v_rcp_f32_e32 v93, v93
	v_pk_mul_f32 v[94:95], v[96:97], v[100:101] op_sel_hi:[0,1]
	v_pk_mul_f32 v[88:89], v[88:89], v[94:95]
	v_pk_mul_f32 v[94:95], v[84:85], v[98:99] op_sel_hi:[1,0]
	v_pk_mul_f32 v[92:93], v[96:97], v[92:93] op_sel_hi:[0,1]
	v_exp_f32_e32 v94, v94
	v_exp_f32_e32 v95, v95
	v_pk_mul_f32 v[90:91], v[90:91], v[92:93]
	v_cvt_pk_bf16_f32 v88, v88, v89
	v_pk_mul_f32 v[84:85], v[86:87], v[98:99] op_sel_hi:[1,0]
	v_cvt_pk_bf16_f32 v89, v90, v91
	v_pk_add_f32 v[90:91], v[94:95], 1.0 op_sel_hi:[1,0]
	v_exp_f32_e32 v84, v84
	v_rcp_f32_e32 v90, v90
	v_rcp_f32_e32 v91, v91
	v_exp_f32_e32 v85, v85
	v_pk_mul_f32 v[86:87], v[96:97], v[90:91] op_sel_hi:[0,1]
	v_pk_mul_f32 v[80:81], v[80:81], v[86:87]
	s_nop 0
	v_cvt_pk_bf16_f32 v90, v80, v81
	v_pk_add_f32 v[80:81], v[84:85], 1.0 op_sel_hi:[1,0]
	v_ffbh_u32_e32 v84, v151
	v_min_u32_e32 v86, 32, v84
	v_lshlrev_b64 v[84:85], v86, v[150:151]
	v_rcp_f32_e32 v80, v80
	v_rcp_f32_e32 v81, v81
	v_min_u32_e32 v84, 1, v84
	v_or_b32_e32 v84, v85, v84
	v_cvt_f32_u32_e32 v84, v84
	v_pk_mul_f32 v[80:81], v[96:97], v[80:81] op_sel_hi:[0,1]
	v_pk_mul_f32 v[80:81], v[82:83], v[80:81]
	v_sub_u32_e32 v82, 32, v86
	v_ldexp_f32 v82, v84, v82
	v_mul_f32_e32 v82, 0x33800000, v82
	v_fmamk_f32 v82, v82, 0x39800000, v158
	v_mul_f32_e32 v83, 0x4b800000, v82
	v_cmp_gt_f32_e32 vcc, s60, v82
	v_cvt_pk_bf16_f32 v91, v80, v81
	v_mad_i64_i32 v[80:81], s[4:5], v148, s61, v[120:121]
	s_nop 0
	v_cndmask_b32_e32 v82, v82, v83, vcc
	v_rsq_f32_e32 v82, v82
	v_lshl_add_u64 v[80:81], v[80:81], 0, v[116:117]
	ds_bpermute_b32 v230, v232, v80
	ds_bpermute_b32 v231, v232, v81
	ds_bpermute_b32 v226, v232, v88
	ds_bpermute_b32 v227, v232, v89
	ds_bpermute_b32 v228, v232, v90
	ds_bpermute_b32 v229, v232, v91
	s_waitcnt lgkmcnt(0)
	global_store_dwordx4 v[230:231], v[226:229], off
	v_mul_f32_e32 v83, 0x45800000, v82
	v_cndmask_b32_e32 v83, v82, v83, vcc
	v_mul_f32_e32 v82, 0xbfb8aa3b, v83
	v_pk_mul_f32 v[84:85], v[76:77], v[82:83] op_sel_hi:[1,0]
	v_pk_mul_f32 v[76:77], v[78:79], v[82:83] op_sel_hi:[1,0]
	v_exp_f32_e32 v84, v84
	v_exp_f32_e32 v85, v85
	v_exp_f32_e32 v76, v76
	v_exp_f32_e32 v77, v77
	v_mul_f32_e32 v80, v83, v83
	v_pk_add_f32 v[84:85], v[84:85], 1.0 op_sel_hi:[1,0]
	v_pk_add_f32 v[76:77], v[76:77], 1.0 op_sel_hi:[1,0]
	v_rcp_f32_e32 v84, v84
	v_rcp_f32_e32 v85, v85
	v_rcp_f32_e32 v76, v76
	v_rcp_f32_e32 v77, v77
	v_pk_mul_f32 v[78:79], v[80:81], v[84:85] op_sel_hi:[0,1]
	v_pk_mul_f32 v[72:73], v[72:73], v[78:79]
	v_pk_mul_f32 v[78:79], v[68:69], v[82:83] op_sel_hi:[1,0]
	v_pk_mul_f32 v[76:77], v[80:81], v[76:77] op_sel_hi:[0,1]
	v_exp_f32_e32 v78, v78
	v_exp_f32_e32 v79, v79
	v_pk_mul_f32 v[74:75], v[74:75], v[76:77]
	v_cvt_pk_bf16_f32 v72, v72, v73
	v_pk_mul_f32 v[68:69], v[70:71], v[82:83] op_sel_hi:[1,0]
	v_cvt_pk_bf16_f32 v73, v74, v75
	v_pk_add_f32 v[74:75], v[78:79], 1.0 op_sel_hi:[1,0]
	v_exp_f32_e32 v68, v68
	v_rcp_f32_e32 v74, v74
	v_rcp_f32_e32 v75, v75
	v_exp_f32_e32 v69, v69
	v_pk_mul_f32 v[70:71], v[80:81], v[74:75] op_sel_hi:[0,1]
	v_pk_mul_f32 v[64:65], v[64:65], v[70:71]
	s_nop 0
	v_cvt_pk_bf16_f32 v74, v64, v65
	v_pk_add_f32 v[64:65], v[68:69], 1.0 op_sel_hi:[1,0]
	v_ffbh_u32_e32 v68, v145
	v_min_u32_e32 v70, 32, v68
	v_lshlrev_b64 v[68:69], v70, v[144:145]
	v_rcp_f32_e32 v64, v64
	v_rcp_f32_e32 v65, v65
	v_min_u32_e32 v68, 1, v68
	v_or_b32_e32 v68, v69, v68
	v_cvt_f32_u32_e32 v68, v68
	v_pk_mul_f32 v[64:65], v[80:81], v[64:65] op_sel_hi:[0,1]
	v_pk_mul_f32 v[64:65], v[66:67], v[64:65]
	v_sub_u32_e32 v66, 32, v70
	v_ldexp_f32 v66, v68, v66
	v_mul_f32_e32 v66, 0x33800000, v66
	v_fmamk_f32 v66, v66, 0x39800000, v158
	v_mul_f32_e32 v67, 0x4b800000, v66
	v_cmp_gt_f32_e32 vcc, s60, v66
	v_cvt_pk_bf16_f32 v75, v64, v65
	v_mad_i64_i32 v[64:65], s[4:5], v126, s61, v[120:121]
	s_nop 0
	v_cndmask_b32_e32 v66, v66, v67, vcc
	v_rsq_f32_e32 v66, v66
	v_lshl_add_u64 v[64:65], v[64:65], 0, v[116:117]
	ds_bpermute_b32 v230, v232, v64
	ds_bpermute_b32 v231, v232, v65
	ds_bpermute_b32 v234, v232, v72
	ds_bpermute_b32 v235, v232, v73
	ds_bpermute_b32 v236, v232, v74
	ds_bpermute_b32 v237, v232, v75
	s_waitcnt lgkmcnt(0)
; __device__ __forceinline__ unsigned cvt_pk_bf16(float lo, float hi) { unsigned r; asm volatile("v_cvt_pk_bf16_f32 %0, %1, %2" : "=v"(r) : "v"(lo), "v"(hi)); return r; }
;     __device__ __forceinline__ void operator()(const f32x4 (&acc)[2][2][4][2], const Unit& u, int wr, int wc, int fr, int fq) const {
;     ...
;             for (int m = 0; m < 4; ++m) {
;                 const int row = row0 + ai * HALF + m * 16; const float rs = rsqrtf((float)sq[ai][m] * (1.0f / FIXS) * (1.0f / (float)D) + EPS);
;                 typedef float f2 __attribute__((ext_vector_type(2)));
;                 const float c1 = -1.4426950408889634f * rs, c2 = rs * rs;
;                 u32x4 w; unsigned wq[4];
; #pragma unroll
;                 for (int q = 0; q < 4; ++q) { const f32x4 gg = acc[ai][0][m][q >> 1], uu = acc[ai][1][m][q >> 1];
;                     const f2 g = {gg[2 * (q & 1)], gg[2 * (q & 1) + 1]}, u2 = {uu[2 * (q & 1)], uu[2 * (q & 1) + 1]};
;                     const f2 t = g * c1; const f2 e = {__builtin_amdgcn_exp2f(t.x), __builtin_amdgcn_exp2f(t.y)};
;                     const f2 d = e + 1.0f; const f2 r = {__builtin_amdgcn_rcpf(d.x), __builtin_amdgcn_rcpf(d.y)};
;                     const f2 o = (g * u2) * (r * c2);
;                     wq[q] = cvt_pk_bf16(o.x, o.y); }
;                 w.x = wq[0]; w.y = wq[1]; w.z = wq[2]; w.w = wq[3];
;                 *(u32x4*)(O + (size_t)row * LDF + col0) = w;
;             }
	global_store_dwordx4 v[230:231], v[234:237], off
	v_mul_f32_e32 v67, 0x45800000, v66
	v_cndmask_b32_e32 v67, v66, v67, vcc
	v_mul_f32_e32 v66, 0xbfb8aa3b, v67
	v_pk_mul_f32 v[68:69], v[60:61], v[66:67] op_sel_hi:[1,0]
	v_pk_mul_f32 v[60:61], v[62:63], v[66:67] op_sel_hi:[1,0]
	v_exp_f32_e32 v68, v68
	v_exp_f32_e32 v69, v69
	v_exp_f32_e32 v60, v60
	v_exp_f32_e32 v61, v61
	v_mul_f32_e32 v64, v67, v67
	v_pk_add_f32 v[68:69], v[68:69], 1.0 op_sel_hi:[1,0]
	v_pk_add_f32 v[60:61], v[60:61], 1.0 op_sel_hi:[1,0]
	v_rcp_f32_e32 v68, v68
	v_rcp_f32_e32 v69, v69
	v_rcp_f32_e32 v60, v60
	v_rcp_f32_e32 v61, v61
	v_pk_mul_f32 v[62:63], v[64:65], v[68:69] op_sel_hi:[0,1]
	v_pk_mul_f32 v[56:57], v[56:57], v[62:63]
	v_pk_mul_f32 v[62:63], v[52:53], v[66:67] op_sel_hi:[1,0]
	v_pk_mul_f32 v[60:61], v[64:65], v[60:61] op_sel_hi:[0,1]
	v_exp_f32_e32 v62, v62
	v_exp_f32_e32 v63, v63
	v_pk_mul_f32 v[58:59], v[58:59], v[60:61]
	v_cvt_pk_bf16_f32 v56, v56, v57
	v_pk_mul_f32 v[52:53], v[54:55], v[66:67] op_sel_hi:[1,0]
	v_cvt_pk_bf16_f32 v57, v58, v59
	v_pk_add_f32 v[58:59], v[62:63], 1.0 op_sel_hi:[1,0]
	v_exp_f32_e32 v52, v52
	v_rcp_f32_e32 v58, v58
	v_rcp_f32_e32 v59, v59
	v_exp_f32_e32 v53, v53
	v_pk_mul_f32 v[54:55], v[64:65], v[58:59] op_sel_hi:[0,1]
	v_pk_mul_f32 v[48:49], v[48:49], v[54:55]
	s_nop 0
	v_cvt_pk_bf16_f32 v58, v48, v49
	v_pk_add_f32 v[48:49], v[52:53], 1.0 op_sel_hi:[1,0]
	v_ffbh_u32_e32 v52, v125
	v_min_u32_e32 v54, 32, v52
	v_lshlrev_b64 v[52:53], v54, v[124:125]
	v_rcp_f32_e32 v48, v48
	v_rcp_f32_e32 v49, v49
	v_min_u32_e32 v52, 1, v52
	v_or_b32_e32 v52, v53, v52
	v_cvt_f32_u32_e32 v52, v52
	v_pk_mul_f32 v[48:49], v[64:65], v[48:49] op_sel_hi:[0,1]
	v_pk_mul_f32 v[48:49], v[50:51], v[48:49]
	v_sub_u32_e32 v50, 32, v54
	v_ldexp_f32 v50, v52, v50
	v_mul_f32_e32 v50, 0x33800000, v50
	v_fmamk_f32 v50, v50, 0x39800000, v158
	v_mul_f32_e32 v51, 0x4b800000, v50
	v_cmp_gt_f32_e32 vcc, s60, v50
	v_cvt_pk_bf16_f32 v59, v48, v49
	v_mad_i64_i32 v[48:49], s[4:5], v161, s61, v[120:121]
	s_nop 0
	v_cndmask_b32_e32 v50, v50, v51, vcc
	v_rsq_f32_e32 v50, v50
	v_lshl_add_u64 v[48:49], v[48:49], 0, v[116:117]
	ds_bpermute_b32 v230, v232, v48
	ds_bpermute_b32 v231, v232, v49
	ds_bpermute_b32 v226, v232, v56
	ds_bpermute_b32 v227, v232, v57
	ds_bpermute_b32 v228, v232, v58
	ds_bpermute_b32 v229, v232, v59
	s_waitcnt lgkmcnt(0)
	global_store_dwordx4 v[230:231], v[226:229], off
	v_mul_f32_e32 v51, 0x45800000, v50
	v_cndmask_b32_e32 v51, v50, v51, vcc
	v_mul_f32_e32 v50, 0xbfb8aa3b, v51
	v_pk_mul_f32 v[52:53], v[44:45], v[50:51] op_sel_hi:[1,0]
	v_pk_mul_f32 v[44:45], v[46:47], v[50:51] op_sel_hi:[1,0]
	v_exp_f32_e32 v52, v52
	v_exp_f32_e32 v53, v53
	v_exp_f32_e32 v44, v44
	v_exp_f32_e32 v45, v45
	v_mul_f32_e32 v48, v51, v51
	v_pk_add_f32 v[52:53], v[52:53], 1.0 op_sel_hi:[1,0]
	v_pk_add_f32 v[44:45], v[44:45], 1.0 op_sel_hi:[1,0]
	v_rcp_f32_e32 v52, v52
	v_rcp_f32_e32 v53, v53
	v_rcp_f32_e32 v44, v44
	v_rcp_f32_e32 v45, v45
	v_pk_mul_f32 v[46:47], v[48:49], v[52:53] op_sel_hi:[0,1]
	v_pk_mul_f32 v[40:41], v[40:41], v[46:47]
	v_pk_mul_f32 v[46:47], v[36:37], v[50:51] op_sel_hi:[1,0]
	v_pk_mul_f32 v[44:45], v[48:49], v[44:45] op_sel_hi:[0,1]
	v_exp_f32_e32 v46, v46
	v_exp_f32_e32 v47, v47
	v_pk_mul_f32 v[42:43], v[42:43], v[44:45]
	v_cvt_pk_bf16_f32 v40, v40, v41
	v_pk_mul_f32 v[36:37], v[38:39], v[50:51] op_sel_hi:[1,0]
	v_cvt_pk_bf16_f32 v41, v42, v43
	v_pk_add_f32 v[42:43], v[46:47], 1.0 op_sel_hi:[1,0]
	v_exp_f32_e32 v36, v36
	v_rcp_f32_e32 v42, v42
	v_rcp_f32_e32 v43, v43
	v_exp_f32_e32 v37, v37
	v_pk_mul_f32 v[38:39], v[48:49], v[42:43] op_sel_hi:[0,1]
	v_pk_mul_f32 v[32:33], v[32:33], v[38:39]
	s_nop 0
	v_cvt_pk_bf16_f32 v42, v32, v33
	v_pk_add_f32 v[32:33], v[36:37], 1.0 op_sel_hi:[1,0]
	v_ffbh_u32_e32 v36, v123
	v_min_u32_e32 v38, 32, v36
	v_lshlrev_b64 v[36:37], v38, v[122:123]
	v_rcp_f32_e32 v32, v32
	v_rcp_f32_e32 v33, v33
	v_min_u32_e32 v36, 1, v36
	v_or_b32_e32 v36, v37, v36
	v_cvt_f32_u32_e32 v36, v36
	v_pk_mul_f32 v[32:33], v[48:49], v[32:33] op_sel_hi:[0,1]
	v_pk_mul_f32 v[32:33], v[34:35], v[32:33]
	v_sub_u32_e32 v34, 32, v38
	v_ldexp_f32 v34, v36, v34
	v_mul_f32_e32 v34, 0x33800000, v34
	v_fmamk_f32 v34, v34, 0x39800000, v158
	v_mul_f32_e32 v35, 0x4b800000, v34
	v_cmp_gt_f32_e32 vcc, s60, v34
	v_cvt_pk_bf16_f32 v43, v32, v33
	v_mad_i64_i32 v[32:33], s[4:5], v160, s61, v[120:121]
	s_nop 0
	v_cndmask_b32_e32 v34, v34, v35, vcc
	v_rsq_f32_e32 v34, v34
	v_lshl_add_u64 v[32:33], v[32:33], 0, v[116:117]
	ds_bpermute_b32 v230, v232, v32
	ds_bpermute_b32 v231, v232, v33
	ds_bpermute_b32 v234, v232, v40
	ds_bpermute_b32 v235, v232, v41
	ds_bpermute_b32 v236, v232, v42
	ds_bpermute_b32 v237, v232, v43
	s_waitcnt lgkmcnt(0)
; __device__ __forceinline__ unsigned cvt_pk_bf16(float lo, float hi) { unsigned r; asm volatile("v_cvt_pk_bf16_f32 %0, %1, %2" : "=v"(r) : "v"(lo), "v"(hi)); return r; }
;     __device__ __forceinline__ void operator()(const f32x4 (&acc)[2][2][4][2], const Unit& u, int wr, int wc, int fr, int fq) const {
;     ...
;             for (int m = 0; m < 4; ++m) {
;                 const int row = row0 + ai * HALF + m * 16; const float rs = rsqrtf((float)sq[ai][m] * (1.0f / FIXS) * (1.0f / (float)D) + EPS);
;                 typedef float f2 __attribute__((ext_vector_type(2)));
;                 const float c1 = -1.4426950408889634f * rs, c2 = rs * rs;
;                 u32x4 w; unsigned wq[4];
; #pragma unroll
;                 for (int q = 0; q < 4; ++q) { const f32x4 gg = acc[ai][0][m][q >> 1], uu = acc[ai][1][m][q >> 1];
;                     const f2 g = {gg[2 * (q & 1)], gg[2 * (q & 1) + 1]}, u2 = {uu[2 * (q & 1)], uu[2 * (q & 1) + 1]};
;                     const f2 t = g * c1; const f2 e = {__builtin_amdgcn_exp2f(t.x), __builtin_amdgcn_exp2f(t.y)};
;                     const f2 d = e + 1.0f; const f2 r = {__builtin_amdgcn_rcpf(d.x), __builtin_amdgcn_rcpf(d.y)};
;                     const f2 o = (g * u2) * (r * c2);
;                     wq[q] = cvt_pk_bf16(o.x, o.y); }
;                 w.x = wq[0]; w.y = wq[1]; w.z = wq[2]; w.w = wq[3];
;                 *(u32x4*)(O + (size_t)row * LDF + col0) = w;
;             }
	global_store_dwordx4 v[230:231], v[234:237], off
	v_mul_f32_e32 v35, 0x45800000, v34
	v_cndmask_b32_e32 v35, v34, v35, vcc
	v_mul_f32_e32 v34, 0xbfb8aa3b, v35
	v_pk_mul_f32 v[36:37], v[28:29], v[34:35] op_sel_hi:[1,0]
	v_pk_mul_f32 v[28:29], v[30:31], v[34:35] op_sel_hi:[1,0]
	v_exp_f32_e32 v36, v36
	v_exp_f32_e32 v37, v37
	v_exp_f32_e32 v28, v28
	v_exp_f32_e32 v29, v29
	v_mul_f32_e32 v32, v35, v35
	v_pk_add_f32 v[36:37], v[36:37], 1.0 op_sel_hi:[1,0]
	v_pk_add_f32 v[28:29], v[28:29], 1.0 op_sel_hi:[1,0]
	v_rcp_f32_e32 v36, v36
	v_rcp_f32_e32 v37, v37
	v_rcp_f32_e32 v28, v28
	v_rcp_f32_e32 v29, v29
	v_pk_mul_f32 v[30:31], v[32:33], v[36:37] op_sel_hi:[0,1]
	v_pk_mul_f32 v[24:25], v[24:25], v[30:31]
	v_pk_mul_f32 v[30:31], v[20:21], v[34:35] op_sel_hi:[1,0]
	v_pk_mul_f32 v[28:29], v[32:33], v[28:29] op_sel_hi:[0,1]
	v_exp_f32_e32 v30, v30
	v_exp_f32_e32 v31, v31
	v_pk_mul_f32 v[26:27], v[26:27], v[28:29]
	v_cvt_pk_bf16_f32 v24, v24, v25
	v_pk_mul_f32 v[20:21], v[22:23], v[34:35] op_sel_hi:[1,0]
	v_cvt_pk_bf16_f32 v25, v26, v27
	v_pk_add_f32 v[26:27], v[30:31], 1.0 op_sel_hi:[1,0]
	v_exp_f32_e32 v20, v20
	v_rcp_f32_e32 v26, v26
	v_rcp_f32_e32 v27, v27
	v_exp_f32_e32 v21, v21
	v_pk_mul_f32 v[22:23], v[32:33], v[26:27] op_sel_hi:[0,1]
	v_pk_mul_f32 v[16:17], v[16:17], v[22:23]
	s_nop 0
	v_cvt_pk_bf16_f32 v26, v16, v17
	v_pk_add_f32 v[16:17], v[20:21], 1.0 op_sel_hi:[1,0]
	v_ffbh_u32_e32 v20, v119
	v_min_u32_e32 v22, 32, v20
	v_lshlrev_b64 v[20:21], v22, v[118:119]
	v_rcp_f32_e32 v16, v16
	v_rcp_f32_e32 v17, v17
	v_min_u32_e32 v20, 1, v20
	v_or_b32_e32 v20, v21, v20
	v_cvt_f32_u32_e32 v20, v20
	v_pk_mul_f32 v[16:17], v[32:33], v[16:17] op_sel_hi:[0,1]
	v_pk_mul_f32 v[16:17], v[18:19], v[16:17]
	v_sub_u32_e32 v18, 32, v22
	v_ldexp_f32 v18, v20, v18
	v_mul_f32_e32 v18, 0x33800000, v18
	v_fmamk_f32 v18, v18, 0x39800000, v158
	v_mul_f32_e32 v19, 0x4b800000, v18
	v_cmp_gt_f32_e32 vcc, s60, v18
	v_cvt_pk_bf16_f32 v27, v16, v17
	v_mad_i64_i32 v[16:17], s[4:5], v159, s61, v[120:121]
	s_nop 0
	v_cndmask_b32_e32 v18, v18, v19, vcc
	v_rsq_f32_e32 v18, v18
	v_lshl_add_u64 v[16:17], v[16:17], 0, v[116:117]
	ds_bpermute_b32 v230, v232, v16
	ds_bpermute_b32 v231, v232, v17
	ds_bpermute_b32 v226, v232, v24
	ds_bpermute_b32 v227, v232, v25
	ds_bpermute_b32 v228, v232, v26
	ds_bpermute_b32 v229, v232, v27
	s_waitcnt lgkmcnt(0)
	global_store_dwordx4 v[230:231], v[226:229], off
	v_mul_f32_e32 v19, 0x45800000, v18
	v_cndmask_b32_e32 v19, v18, v19, vcc
	v_mul_f32_e32 v18, 0xbfb8aa3b, v19
	v_pk_mul_f32 v[20:21], v[12:13], v[18:19] op_sel_hi:[1,0]
	v_pk_mul_f32 v[12:13], v[14:15], v[18:19] op_sel_hi:[1,0]
	v_exp_f32_e32 v20, v20
	v_exp_f32_e32 v21, v21
	v_exp_f32_e32 v12, v12
	v_exp_f32_e32 v13, v13
	v_mul_f32_e32 v16, v19, v19
	v_pk_add_f32 v[20:21], v[20:21], 1.0 op_sel_hi:[1,0]
	s_and_b64 vcc, exec, s[2:3]
	v_rcp_f32_e32 v20, v20
	v_rcp_f32_e32 v21, v21
	v_pk_add_f32 v[12:13], v[12:13], 1.0 op_sel_hi:[1,0]
	s_mov_b64 s[2:3], -1
	v_rcp_f32_e32 v12, v12
	v_rcp_f32_e32 v13, v13
	v_pk_mul_f32 v[14:15], v[16:17], v[20:21] op_sel_hi:[0,1]
	v_pk_mul_f32 v[8:9], v[8:9], v[14:15]
	v_pk_mul_f32 v[14:15], v[4:5], v[18:19] op_sel_hi:[1,0]
	v_pk_mul_f32 v[12:13], v[16:17], v[12:13] op_sel_hi:[0,1]
	v_exp_f32_e32 v14, v14
	v_exp_f32_e32 v15, v15
	v_pk_mul_f32 v[10:11], v[10:11], v[12:13]
	v_pk_mul_f32 v[12:13], v[6:7], v[18:19] op_sel_hi:[1,0]
	v_cvt_pk_bf16_f32 v8, v8, v9
	v_cvt_pk_bf16_f32 v9, v10, v11
	v_pk_add_f32 v[10:11], v[14:15], 1.0 op_sel_hi:[1,0]
	v_exp_f32_e32 v12, v12
	v_exp_f32_e32 v13, v13
	v_rcp_f32_e32 v10, v10
	v_rcp_f32_e32 v11, v11
	v_pk_add_f32 v[4:5], v[12:13], 1.0 op_sel_hi:[1,0]
	s_nop 0
	v_rcp_f32_e32 v4, v4
	v_rcp_f32_e32 v5, v5
	v_pk_mul_f32 v[6:7], v[16:17], v[10:11] op_sel_hi:[0,1]
	v_pk_mul_f32 v[0:1], v[0:1], v[6:7]
	s_nop 0
	v_cvt_pk_bf16_f32 v10, v0, v1
	v_pk_mul_f32 v[0:1], v[16:17], v[4:5] op_sel_hi:[0,1]
	v_pk_mul_f32 v[0:1], v[2:3], v[0:1]
	s_nop 0
	v_cvt_pk_bf16_f32 v11, v0, v1
	v_mad_i64_i32 v[0:1], s[4:5], v147, s61, v[120:121]
	v_lshl_add_u64 v[0:1], v[0:1], 0, v[116:117]
	ds_bpermute_b32 v230, v232, v0
	ds_bpermute_b32 v231, v232, v1
	ds_bpermute_b32 v234, v232, v8
	ds_bpermute_b32 v235, v232, v9
	ds_bpermute_b32 v236, v232, v10
	ds_bpermute_b32 v237, v232, v11
	s_waitcnt lgkmcnt(0)
	global_store_dwordx4 v[230:231], v[234:237], off
	s_cbranch_vccnz .LBB0_225
	s_andn2_b64 vcc, exec, s[38:39]
	s_cbranch_vccnz .LBB0_224
	s_barrier
	s_branch .LBB0_224

; __device__ __forceinline__ unsigned cvt_pk_bf16(float lo, float hi) { unsigned r; asm volatile("v_cvt_pk_bf16_f32 %0, %1, %2" : "=v"(r) : "v"(lo), "v"(hi)); return r; }
;     __device__ __forceinline__ void operator()(const f32x4 (&acc)[2][2][4][2], const Unit& u, int wr, int wc, int fr, int fq) const {
;         const int row0 = u.pm * BM + wr * 64 + fr, col0 = u.pn * HALF + wc * 32 + 8 * fq;
;         unsigned long long sq[2][4];
; #pragma unroll
;         for (int ai = 0; ai < 2; ++ai)
; #pragma unroll
;             for (int m = 0; m < 4; ++m) sq[ai][m] = ssq[row0 + ai * HALF + m * 16];
; #pragma unroll
;         for (int ai = 0; ai < 2; ++ai)
; #pragma unroll
;             for (int m = 0; m < 4; ++m) {
;                 const int row = row0 + ai * HALF + m * 16; const float rs = rsqrtf((float)sq[ai][m] * (1.0f / FIXS) * (1.0f / (float)D) + EPS);
;                 typedef float f2 __attribute__((ext_vector_type(2)));
;                 const float c1 = -1.4426950408889634f * rs, c2 = rs * rs;
;                 u32x4 w; unsigned wq[4];
; #pragma unroll
;                 for (int q = 0; q < 4; ++q) { const f32x4 gg = acc[ai][0][m][q >> 1], uu = acc[ai][1][m][q >> 1];
;                     const f2 g = {gg[2 * (q & 1)], gg[2 * (q & 1) + 1]}, u2 = {uu[2 * (q & 1)], uu[2 * (q & 1) + 1]};
;                     const f2 t = g * c1; const f2 e = {__builtin_amdgcn_exp2f(t.x), __builtin_amdgcn_exp2f(t.y)};
;                     const f2 d = e + 1.0f; const f2 r = {__builtin_amdgcn_rcpf(d.x), __builtin_amdgcn_rcpf(d.y)};
;                     const f2 o = (g * u2) * (r * c2);
;                     wq[q] = cvt_pk_bf16(o.x, o.y); }
;                 w.x = wq[0]; w.y = wq[1]; w.z = wq[2]; w.w = wq[3];
;                 *(u32x4*)(O + (size_t)row * LDF + col0) = w;
;             }
;     }
.LBB0_1136:
	v_mbcnt_lo_u32_b32 v233, -1, 0
	v_mbcnt_hi_u32_b32 v233, -1, v233
	v_lshrrev_b32_e32 v232, 2, v233
	v_and_b32_e32 v233, 3, v233
	v_lshl_add_u32 v232, v233, 4, v232
	v_lshlrev_b32_e32 v232, 2, v232
	v_lshl_add_u32 v144, s20, 8, v152
	v_ashrrev_i32_e32 v145, 31, v144
	v_lshl_add_u64 v[162:163], v[144:145], 3, s[34:35]
	v_or_b32_e32 v146, 16, v144
	global_load_dwordx2 v[164:165], v[162:163], off
	v_ashrrev_i32_e32 v147, 31, v146
	v_lshl_add_u64 v[148:149], v[146:147], 3, s[34:35]
	global_load_dwordx2 v[166:167], v[148:149], off
	v_lshl_add_u32 v150, s21, 7, v154
	v_pk_mul_f32 v[168:169], v[114:115], v[126:127]
	v_or_b32_e32 v148, 32, v144
	v_or_b32_e32 v126, 48, v144
	v_ashrrev_i32_e32 v151, 31, v150
	v_ashrrev_i32_e32 v149, 31, v148
	v_ashrrev_i32_e32 v127, 31, v126
	v_pk_mul_f32 v[174:175], v[108:109], v[120:121]
	v_mov_b64_e32 v[120:121], s[30:31]
	v_pk_mul_f32 v[176:177], v[106:107], v[118:119]
	v_pk_mul_f32 v[178:179], v[104:105], v[116:117]
	v_lshlrev_b64 v[116:117], 1, v[150:151]
	v_lshl_add_u64 v[118:119], v[148:149], 3, s[34:35]
	v_lshl_add_u64 v[150:151], v[126:127], 3, s[34:35]
	v_pk_mul_f32 v[170:171], v[112:113], v[124:125]
	v_pk_mul_f32 v[172:173], v[110:111], v[122:123]
	v_add_u32_e32 v161, 0x80, v144
	v_add_u32_e32 v160, 0x90, v144
	v_add_u32_e32 v159, 0xa0, v144
	v_add_u32_e32 v147, 0xb0, v144
	v_mad_i64_i32 v[180:181], s[4:5], v144, s58, v[120:121]
	global_load_dwordx2 v[144:145], v[162:163], off offset:1024
	global_load_dwordx2 v[124:125], v[162:163], off offset:1152
	global_load_dwordx2 v[122:123], v[162:163], off offset:1280
	global_load_dwordx2 v[182:183], v[118:119], off
	s_nop 0
	global_load_dwordx2 v[150:151], v[150:151], off
	s_nop 0
	global_load_dwordx2 v[118:119], v[162:163], off offset:1408
	v_pk_mul_f32 v[96:97], v[100:101], v[96:97]
	v_pk_mul_f32 v[98:99], v[102:103], v[98:99]
	v_pk_mul_f32 v[88:89], v[92:93], v[88:89]
	v_pk_mul_f32 v[90:91], v[94:95], v[90:91]
	v_pk_mul_f32 v[80:81], v[84:85], v[80:81]
	v_pk_mul_f32 v[82:83], v[86:87], v[82:83]
	v_pk_mul_f32 v[72:73], v[76:77], v[72:73]
	v_pk_mul_f32 v[74:75], v[78:79], v[74:75]
	v_pk_mul_f32 v[64:65], v[68:69], v[64:65]
	v_pk_mul_f32 v[66:67], v[70:71], v[66:67]
	v_pk_mul_f32 v[56:57], v[60:61], v[56:57]
	v_pk_mul_f32 v[58:59], v[62:63], v[58:59]
	v_pk_mul_f32 v[48:49], v[52:53], v[48:49]
	v_pk_mul_f32 v[50:51], v[54:55], v[50:51]
	v_pk_mul_f32 v[40:41], v[44:45], v[40:41]
	v_pk_mul_f32 v[42:43], v[46:47], v[42:43]
	v_pk_mul_f32 v[32:33], v[36:37], v[32:33]
	v_pk_mul_f32 v[34:35], v[38:39], v[34:35]
	v_pk_mul_f32 v[24:25], v[28:29], v[24:25]
	v_pk_mul_f32 v[26:27], v[30:31], v[26:27]
	v_pk_mul_f32 v[16:17], v[20:21], v[16:17]
	v_pk_mul_f32 v[18:19], v[22:23], v[18:19]
	v_pk_mul_f32 v[8:9], v[12:13], v[8:9]
	v_pk_mul_f32 v[10:11], v[14:15], v[10:11]
	v_pk_mul_f32 v[0:1], v[4:5], v[0:1]
	v_pk_mul_f32 v[2:3], v[6:7], v[2:3]
	s_waitcnt vmcnt(0)
	v_ffbh_u32_e32 v127, v165
	v_min_u32_e32 v127, 32, v127
	v_lshlrev_b64 v[162:163], v127, v[164:165]
	v_ffbh_u32_e32 v149, v167
	v_min_u32_e32 v149, 32, v149
	v_min_u32_e32 v162, 1, v162
	v_lshlrev_b64 v[164:165], v149, v[166:167]
	v_or_b32_e32 v162, v163, v162
	v_min_u32_e32 v163, 1, v164
	v_cvt_f32_u32_e32 v162, v162
	v_or_b32_e32 v163, v165, v163
	v_cvt_f32_u32_e32 v163, v163
	v_sub_u32_e32 v127, 32, v127
	v_ldexp_f32 v127, v162, v127
	v_sub_u32_e32 v149, 32, v149
	v_mul_f32_e32 v127, 0x33800000, v127
	v_ldexp_f32 v149, v163, v149
	v_fmamk_f32 v127, v127, 0x39800000, v158
	v_mul_f32_e32 v149, 0x33800000, v149
	v_mul_f32_e32 v162, 0x4b800000, v127
	v_cmp_gt_f32_e32 vcc, s57, v127
	v_fmamk_f32 v149, v149, 0x39800000, v158
	v_cmp_gt_f32_e64 s[4:5], s57, v149
	v_cndmask_b32_e32 v127, v127, v162, vcc
	v_mul_f32_e32 v162, 0x4b800000, v149
	v_rsq_f32_e32 v127, v127
	v_cndmask_b32_e64 v149, v149, v162, s[4:5]
	v_rsq_f32_e32 v149, v149
	v_lshl_add_u64 v[162:163], v[180:181], 0, v[116:117]
	v_mul_f32_e32 v164, 0x45800000, v127
	v_cndmask_b32_e32 v127, v127, v164, vcc
	v_mul_f32_e32 v165, 0x45800000, v149
	v_mul_f32_e32 v164, 0xbfb8aa3b, v127
	v_pk_mul_f32 v[112:113], v[112:113], v[164:165] op_sel_hi:[1,0]
	v_pk_mul_f32 v[114:115], v[114:115], v[164:165] op_sel_hi:[1,0]
	v_pk_mul_f32 v[108:109], v[108:109], v[164:165] op_sel_hi:[1,0]
	v_pk_mul_f32 v[110:111], v[110:111], v[164:165] op_sel_hi:[1,0]
	v_exp_f32_e32 v112, v112
	v_exp_f32_e32 v113, v113
	v_exp_f32_e32 v114, v114
	v_exp_f32_e32 v115, v115
	v_mul_f32_e32 v166, v127, v127
	v_cndmask_b32_e64 v127, v149, v165, s[4:5]
	v_exp_f32_e32 v108, v108
	v_exp_f32_e32 v109, v109
	v_exp_f32_e32 v110, v110
	v_exp_f32_e32 v111, v111
	v_mul_f32_e32 v164, 0xbfb8aa3b, v127
	v_pk_mul_f32 v[104:105], v[104:105], v[164:165] op_sel_hi:[1,0]
	v_pk_mul_f32 v[184:185], v[106:107], v[164:165] op_sel_hi:[1,0]
	v_exp_f32_e32 v104, v104
	v_exp_f32_e32 v105, v105
	v_pk_add_f32 v[106:107], v[112:113], 1.0 op_sel_hi:[1,0]
	v_pk_add_f32 v[112:113], v[114:115], 1.0 op_sel_hi:[1,0]
	v_pk_add_f32 v[108:109], v[108:109], 1.0 op_sel_hi:[1,0]
	v_pk_add_f32 v[110:111], v[110:111], 1.0 op_sel_hi:[1,0]
	v_rcp_f32_e32 v106, v106
	v_rcp_f32_e32 v107, v107
	v_rcp_f32_e32 v112, v112
	v_rcp_f32_e32 v113, v113
	v_rcp_f32_e32 v108, v108
	v_rcp_f32_e32 v109, v109
	v_rcp_f32_e32 v110, v110
	v_rcp_f32_e32 v111, v111
	v_exp_f32_e32 v184, v184
	v_pk_add_f32 v[104:105], v[104:105], 1.0 op_sel_hi:[1,0]
	v_exp_f32_e32 v185, v185
	v_rcp_f32_e32 v114, v104
	v_rcp_f32_e32 v115, v105
	v_pk_mul_f32 v[104:105], v[166:167], v[106:107] op_sel_hi:[0,1]
	v_pk_mul_f32 v[106:107], v[166:167], v[112:113] op_sel_hi:[0,1]
	v_pk_mul_f32 v[108:109], v[166:167], v[108:109] op_sel_hi:[0,1]
	v_pk_mul_f32 v[110:111], v[166:167], v[110:111] op_sel_hi:[0,1]
	v_pk_mul_f32 v[104:105], v[170:171], v[104:105]
	v_pk_mul_f32 v[106:107], v[168:169], v[106:107]
	v_pk_mul_f32 v[108:109], v[174:175], v[108:109]
	v_pk_mul_f32 v[110:111], v[172:173], v[110:111]
	v_cvt_pk_bf16_f32 v104, v104, v105
	v_cvt_pk_bf16_f32 v105, v106, v107
	v_cvt_pk_bf16_f32 v106, v108, v109
	v_pk_mul_f32 v[108:109], v[100:101], v[164:165] op_sel_hi:[1,0]
	v_cvt_pk_bf16_f32 v107, v110, v111
	ds_bpermute_b32 v230, v232, v162
	ds_bpermute_b32 v231, v232, v163
	ds_bpermute_b32 v226, v232, v104
	ds_bpermute_b32 v227, v232, v105
	ds_bpermute_b32 v228, v232, v106
	ds_bpermute_b32 v229, v232, v107
	s_waitcnt lgkmcnt(0)
; __device__ __forceinline__ unsigned cvt_pk_bf16(float lo, float hi) { unsigned r; asm volatile("v_cvt_pk_bf16_f32 %0, %1, %2" : "=v"(r) : "v"(lo), "v"(hi)); return r; }
;     __device__ __forceinline__ void operator()(const f32x4 (&acc)[2][2][4][2], const Unit& u, int wr, int wc, int fr, int fq) const {
;     ...
;                 const int row = row0 + ai * HALF + m * 16; const float rs = rsqrtf((float)sq[ai][m] * (1.0f / FIXS) * (1.0f / (float)D) + EPS);
;                 typedef float f2 __attribute__((ext_vector_type(2)));
;                 const float c1 = -1.4426950408889634f * rs, c2 = rs * rs;
;                 u32x4 w; unsigned wq[4];
; #pragma unroll
;                 for (int q = 0; q < 4; ++q) { const f32x4 gg = acc[ai][0][m][q >> 1], uu = acc[ai][1][m][q >> 1];
;                     const f2 g = {gg[2 * (q & 1)], gg[2 * (q & 1) + 1]}, u2 = {uu[2 * (q & 1)], uu[2 * (q & 1) + 1]};
;                     const f2 t = g * c1; const f2 e = {__builtin_amdgcn_exp2f(t.x), __builtin_amdgcn_exp2f(t.y)};
;                     const f2 d = e + 1.0f; const f2 r = {__builtin_amdgcn_rcpf(d.x), __builtin_amdgcn_rcpf(d.y)};
;                     const f2 o = (g * u2) * (r * c2);
;                     wq[q] = cvt_pk_bf16(o.x, o.y); }
;                 w.x = wq[0]; w.y = wq[1]; w.z = wq[2]; w.w = wq[3];
;                 *(u32x4*)(O + (size_t)row * LDF + col0) = w;
	global_store_dwordx4 v[230:231], v[226:229], off
	v_exp_f32_e32 v108, v108
	v_exp_f32_e32 v109, v109
	v_pk_add_f32 v[106:107], v[184:185], 1.0 op_sel_hi:[1,0]
	v_mul_f32_e32 v180, v127, v127
	v_rcp_f32_e32 v106, v106
	v_rcp_f32_e32 v107, v107
	v_pk_mul_f32 v[104:105], v[180:181], v[114:115] op_sel_hi:[0,1]
	v_pk_mul_f32 v[104:105], v[178:179], v[104:105]
	v_pk_mul_f32 v[100:101], v[102:103], v[164:165] op_sel_hi:[1,0]
	v_pk_mul_f32 v[106:107], v[180:181], v[106:107] op_sel_hi:[0,1]
	v_pk_mul_f32 v[106:107], v[176:177], v[106:107]
	v_cvt_pk_bf16_f32 v104, v104, v105
	v_exp_f32_e32 v100, v100
	v_cvt_pk_bf16_f32 v105, v106, v107
	v_pk_add_f32 v[106:107], v[108:109], 1.0 op_sel_hi:[1,0]
	v_exp_f32_e32 v101, v101
	v_rcp_f32_e32 v106, v106
	v_rcp_f32_e32 v107, v107
	s_nop 0
	v_pk_mul_f32 v[102:103], v[180:181], v[106:107] op_sel_hi:[0,1]
	v_pk_mul_f32 v[96:97], v[96:97], v[102:103]
	s_nop 0
	v_cvt_pk_bf16_f32 v106, v96, v97
	v_pk_add_f32 v[96:97], v[100:101], 1.0 op_sel_hi:[1,0]
	v_ffbh_u32_e32 v100, v183
	v_min_u32_e32 v102, 32, v100
	v_lshlrev_b64 v[100:101], v102, v[182:183]
	v_rcp_f32_e32 v96, v96
	v_rcp_f32_e32 v97, v97
	v_min_u32_e32 v100, 1, v100
	v_or_b32_e32 v100, v101, v100
	v_cvt_f32_u32_e32 v100, v100
	v_pk_mul_f32 v[96:97], v[180:181], v[96:97] op_sel_hi:[0,1]
	v_pk_mul_f32 v[96:97], v[98:99], v[96:97]
	v_sub_u32_e32 v98, 32, v102
	v_ldexp_f32 v98, v100, v98
	v_mul_f32_e32 v98, 0x33800000, v98
	v_fmamk_f32 v98, v98, 0x39800000, v158
	v_mul_f32_e32 v99, 0x4b800000, v98
	v_cmp_gt_f32_e32 vcc, s57, v98
	v_cvt_pk_bf16_f32 v107, v96, v97
	v_mad_i64_i32 v[96:97], s[4:5], v146, s58, v[120:121]
	s_nop 0
	v_cndmask_b32_e32 v98, v98, v99, vcc
	v_rsq_f32_e32 v98, v98
	v_lshl_add_u64 v[96:97], v[96:97], 0, v[116:117]
	ds_bpermute_b32 v230, v232, v96
	ds_bpermute_b32 v231, v232, v97
	ds_bpermute_b32 v234, v232, v104
	ds_bpermute_b32 v235, v232, v105
	ds_bpermute_b32 v236, v232, v106
	ds_bpermute_b32 v237, v232, v107
	s_waitcnt lgkmcnt(0)
	global_store_dwordx4 v[230:231], v[234:237], off
	v_mul_f32_e32 v99, 0x45800000, v98
	v_cndmask_b32_e32 v99, v98, v99, vcc
	v_mul_f32_e32 v98, 0xbfb8aa3b, v99
	v_pk_mul_f32 v[100:101], v[92:93], v[98:99] op_sel_hi:[1,0]
	v_pk_mul_f32 v[92:93], v[94:95], v[98:99] op_sel_hi:[1,0]
	v_exp_f32_e32 v100, v100
	v_exp_f32_e32 v101, v101
	v_exp_f32_e32 v92, v92
	v_exp_f32_e32 v93, v93
	v_mul_f32_e32 v96, v99, v99
	v_pk_add_f32 v[100:101], v[100:101], 1.0 op_sel_hi:[1,0]
	v_pk_add_f32 v[92:93], v[92:93], 1.0 op_sel_hi:[1,0]
	v_rcp_f32_e32 v100, v100
	v_rcp_f32_e32 v101, v101
	v_rcp_f32_e32 v92, v92
	v_rcp_f32_e32 v93, v93
	v_pk_mul_f32 v[94:95], v[96:97], v[100:101] op_sel_hi:[0,1]
	v_pk_mul_f32 v[88:89], v[88:89], v[94:95]
	v_pk_mul_f32 v[94:95], v[84:85], v[98:99] op_sel_hi:[1,0]
	v_pk_mul_f32 v[92:93], v[96:97], v[92:93] op_sel_hi:[0,1]
	v_exp_f32_e32 v94, v94
	v_exp_f32_e32 v95, v95
	v_pk_mul_f32 v[90:91], v[90:91], v[92:93]
	v_cvt_pk_bf16_f32 v88, v88, v89
	v_pk_mul_f32 v[84:85], v[86:87], v[98:99] op_sel_hi:[1,0]
	v_cvt_pk_bf16_f32 v89, v90, v91
	v_pk_add_f32 v[90:91], v[94:95], 1.0 op_sel_hi:[1,0]
	v_exp_f32_e32 v84, v84
	v_rcp_f32_e32 v90, v90
	v_rcp_f32_e32 v91, v91
	v_exp_f32_e32 v85, v85
	v_pk_mul_f32 v[86:87], v[96:97], v[90:91] op_sel_hi:[0,1]
	v_pk_mul_f32 v[80:81], v[80:81], v[86:87]
	s_nop 0
	v_cvt_pk_bf16_f32 v90, v80, v81
	v_pk_add_f32 v[80:81], v[84:85], 1.0 op_sel_hi:[1,0]
	v_ffbh_u32_e32 v84, v151
	v_min_u32_e32 v86, 32, v84
	v_lshlrev_b64 v[84:85], v86, v[150:151]
	v_rcp_f32_e32 v80, v80
	v_rcp_f32_e32 v81, v81
	v_min_u32_e32 v84, 1, v84
	v_or_b32_e32 v84, v85, v84
	v_cvt_f32_u32_e32 v84, v84
	v_pk_mul_f32 v[80:81], v[96:97], v[80:81] op_sel_hi:[0,1]
	v_pk_mul_f32 v[80:81], v[82:83], v[80:81]
	v_sub_u32_e32 v82, 32, v86
	v_ldexp_f32 v82, v84, v82
	v_mul_f32_e32 v82, 0x33800000, v82
	v_fmamk_f32 v82, v82, 0x39800000, v158
	v_mul_f32_e32 v83, 0x4b800000, v82
	v_cmp_gt_f32_e32 vcc, s57, v82
	v_cvt_pk_bf16_f32 v91, v80, v81
	v_mad_i64_i32 v[80:81], s[4:5], v148, s58, v[120:121]
	s_nop 0
	v_cndmask_b32_e32 v82, v82, v83, vcc
	v_rsq_f32_e32 v82, v82
	v_lshl_add_u64 v[80:81], v[80:81], 0, v[116:117]
	ds_bpermute_b32 v230, v232, v80
	ds_bpermute_b32 v231, v232, v81
	ds_bpermute_b32 v226, v232, v88
	ds_bpermute_b32 v227, v232, v89
	ds_bpermute_b32 v228, v232, v90
	ds_bpermute_b32 v229, v232, v91
	s_waitcnt lgkmcnt(0)
	global_store_dwordx4 v[230:231], v[226:229], off
	v_mul_f32_e32 v83, 0x45800000, v82
	v_cndmask_b32_e32 v83, v82, v83, vcc
	v_mul_f32_e32 v82, 0xbfb8aa3b, v83
	v_pk_mul_f32 v[84:85], v[76:77], v[82:83] op_sel_hi:[1,0]
	v_pk_mul_f32 v[76:77], v[78:79], v[82:83] op_sel_hi:[1,0]
	v_exp_f32_e32 v84, v84
	v_exp_f32_e32 v85, v85
	v_exp_f32_e32 v76, v76
	v_exp_f32_e32 v77, v77
	v_mul_f32_e32 v80, v83, v83
	v_pk_add_f32 v[84:85], v[84:85], 1.0 op_sel_hi:[1,0]
	v_pk_add_f32 v[76:77], v[76:77], 1.0 op_sel_hi:[1,0]
	v_rcp_f32_e32 v84, v84
	v_rcp_f32_e32 v85, v85
	v_rcp_f32_e32 v76, v76
	v_rcp_f32_e32 v77, v77
	v_pk_mul_f32 v[78:79], v[80:81], v[84:85] op_sel_hi:[0,1]
	v_pk_mul_f32 v[72:73], v[72:73], v[78:79]
	v_pk_mul_f32 v[78:79], v[68:69], v[82:83] op_sel_hi:[1,0]
	v_pk_mul_f32 v[76:77], v[80:81], v[76:77] op_sel_hi:[0,1]
	v_exp_f32_e32 v78, v78
	v_exp_f32_e32 v79, v79
	v_pk_mul_f32 v[74:75], v[74:75], v[76:77]
	v_cvt_pk_bf16_f32 v72, v72, v73
	v_pk_mul_f32 v[68:69], v[70:71], v[82:83] op_sel_hi:[1,0]
	v_cvt_pk_bf16_f32 v73, v74, v75
	v_pk_add_f32 v[74:75], v[78:79], 1.0 op_sel_hi:[1,0]
	v_exp_f32_e32 v68, v68
	v_rcp_f32_e32 v74, v74
	v_rcp_f32_e32 v75, v75
	v_exp_f32_e32 v69, v69
	v_pk_mul_f32 v[70:71], v[80:81], v[74:75] op_sel_hi:[0,1]
	v_pk_mul_f32 v[64:65], v[64:65], v[70:71]
	s_nop 0
	v_cvt_pk_bf16_f32 v74, v64, v65
	v_pk_add_f32 v[64:65], v[68:69], 1.0 op_sel_hi:[1,0]
	v_ffbh_u32_e32 v68, v145
	v_min_u32_e32 v70, 32, v68
	v_lshlrev_b64 v[68:69], v70, v[144:145]
	v_rcp_f32_e32 v64, v64
	v_rcp_f32_e32 v65, v65
	v_min_u32_e32 v68, 1, v68
	v_or_b32_e32 v68, v69, v68
	v_cvt_f32_u32_e32 v68, v68
	v_pk_mul_f32 v[64:65], v[80:81], v[64:65] op_sel_hi:[0,1]
	v_pk_mul_f32 v[64:65], v[66:67], v[64:65]
	v_sub_u32_e32 v66, 32, v70
	v_ldexp_f32 v66, v68, v66
	v_mul_f32_e32 v66, 0x33800000, v66
	v_fmamk_f32 v66, v66, 0x39800000, v158
	v_mul_f32_e32 v67, 0x4b800000, v66
	v_cmp_gt_f32_e32 vcc, s57, v66
	v_cvt_pk_bf16_f32 v75, v64, v65
	v_mad_i64_i32 v[64:65], s[4:5], v126, s58, v[120:121]
	s_nop 0
	v_cndmask_b32_e32 v66, v66, v67, vcc
	v_rsq_f32_e32 v66, v66
	v_lshl_add_u64 v[64:65], v[64:65], 0, v[116:117]
	ds_bpermute_b32 v230, v232, v64
	ds_bpermute_b32 v231, v232, v65
	ds_bpermute_b32 v234, v232, v72
	ds_bpermute_b32 v235, v232, v73
	ds_bpermute_b32 v236, v232, v74
	ds_bpermute_b32 v237, v232, v75
	s_waitcnt lgkmcnt(0)
; __device__ __forceinline__ unsigned cvt_pk_bf16(float lo, float hi) { unsigned r; asm volatile("v_cvt_pk_bf16_f32 %0, %1, %2" : "=v"(r) : "v"(lo), "v"(hi)); return r; }
;     __device__ __forceinline__ void operator()(const f32x4 (&acc)[2][2][4][2], const Unit& u, int wr, int wc, int fr, int fq) const {
;     ...
;                 const int row = row0 + ai * HALF + m * 16; const float rs = rsqrtf((float)sq[ai][m] * (1.0f / FIXS) * (1.0f / (float)D) + EPS);
;                 typedef float f2 __attribute__((ext_vector_type(2)));
;                 const float c1 = -1.4426950408889634f * rs, c2 = rs * rs;
;                 u32x4 w; unsigned wq[4];
; #pragma unroll
;                 for (int q = 0; q < 4; ++q) { const f32x4 gg = acc[ai][0][m][q >> 1], uu = acc[ai][1][m][q >> 1];
;                     const f2 g = {gg[2 * (q & 1)], gg[2 * (q & 1) + 1]}, u2 = {uu[2 * (q & 1)], uu[2 * (q & 1) + 1]};
;                     const f2 t = g * c1; const f2 e = {__builtin_amdgcn_exp2f(t.x), __builtin_amdgcn_exp2f(t.y)};
;                     const f2 d = e + 1.0f; const f2 r = {__builtin_amdgcn_rcpf(d.x), __builtin_amdgcn_rcpf(d.y)};
;                     const f2 o = (g * u2) * (r * c2);
;                     wq[q] = cvt_pk_bf16(o.x, o.y); }
;                 w.x = wq[0]; w.y = wq[1]; w.z = wq[2]; w.w = wq[3];
;                 *(u32x4*)(O + (size_t)row * LDF + col0) = w;
	global_store_dwordx4 v[230:231], v[234:237], off
	v_mul_f32_e32 v67, 0x45800000, v66
	v_cndmask_b32_e32 v67, v66, v67, vcc
	v_mul_f32_e32 v66, 0xbfb8aa3b, v67
	v_pk_mul_f32 v[68:69], v[60:61], v[66:67] op_sel_hi:[1,0]
	v_pk_mul_f32 v[60:61], v[62:63], v[66:67] op_sel_hi:[1,0]
	v_exp_f32_e32 v68, v68
	v_exp_f32_e32 v69, v69
	v_exp_f32_e32 v60, v60
	v_exp_f32_e32 v61, v61
	v_mul_f32_e32 v64, v67, v67
	v_pk_add_f32 v[68:69], v[68:69], 1.0 op_sel_hi:[1,0]
	v_pk_add_f32 v[60:61], v[60:61], 1.0 op_sel_hi:[1,0]
	v_rcp_f32_e32 v68, v68
	v_rcp_f32_e32 v69, v69
	v_rcp_f32_e32 v60, v60
	v_rcp_f32_e32 v61, v61
	v_pk_mul_f32 v[62:63], v[64:65], v[68:69] op_sel_hi:[0,1]
	v_pk_mul_f32 v[56:57], v[56:57], v[62:63]
	v_pk_mul_f32 v[62:63], v[52:53], v[66:67] op_sel_hi:[1,0]
	v_pk_mul_f32 v[60:61], v[64:65], v[60:61] op_sel_hi:[0,1]
	v_exp_f32_e32 v62, v62
	v_exp_f32_e32 v63, v63
	v_pk_mul_f32 v[58:59], v[58:59], v[60:61]
	v_cvt_pk_bf16_f32 v56, v56, v57
	v_pk_mul_f32 v[52:53], v[54:55], v[66:67] op_sel_hi:[1,0]
	v_cvt_pk_bf16_f32 v57, v58, v59
	v_pk_add_f32 v[58:59], v[62:63], 1.0 op_sel_hi:[1,0]
	v_exp_f32_e32 v52, v52
	v_rcp_f32_e32 v58, v58
	v_rcp_f32_e32 v59, v59
	v_exp_f32_e32 v53, v53
	v_pk_mul_f32 v[54:55], v[64:65], v[58:59] op_sel_hi:[0,1]
	v_pk_mul_f32 v[48:49], v[48:49], v[54:55]
	s_nop 0
	v_cvt_pk_bf16_f32 v58, v48, v49
	v_pk_add_f32 v[48:49], v[52:53], 1.0 op_sel_hi:[1,0]
	v_ffbh_u32_e32 v52, v125
	v_min_u32_e32 v54, 32, v52
	v_lshlrev_b64 v[52:53], v54, v[124:125]
	v_rcp_f32_e32 v48, v48
	v_rcp_f32_e32 v49, v49
	v_min_u32_e32 v52, 1, v52
	v_or_b32_e32 v52, v53, v52
	v_cvt_f32_u32_e32 v52, v52
	v_pk_mul_f32 v[48:49], v[64:65], v[48:49] op_sel_hi:[0,1]
	v_pk_mul_f32 v[48:49], v[50:51], v[48:49]
	v_sub_u32_e32 v50, 32, v54
	v_ldexp_f32 v50, v52, v50
	v_mul_f32_e32 v50, 0x33800000, v50
	v_fmamk_f32 v50, v50, 0x39800000, v158
	v_mul_f32_e32 v51, 0x4b800000, v50
	v_cmp_gt_f32_e32 vcc, s57, v50
	v_cvt_pk_bf16_f32 v59, v48, v49
	v_mad_i64_i32 v[48:49], s[4:5], v161, s58, v[120:121]
	s_nop 0
	v_cndmask_b32_e32 v50, v50, v51, vcc
	v_rsq_f32_e32 v50, v50
	v_lshl_add_u64 v[48:49], v[48:49], 0, v[116:117]
	ds_bpermute_b32 v230, v232, v48
	ds_bpermute_b32 v231, v232, v49
	ds_bpermute_b32 v226, v232, v56
	ds_bpermute_b32 v227, v232, v57
	ds_bpermute_b32 v228, v232, v58
	ds_bpermute_b32 v229, v232, v59
	s_waitcnt lgkmcnt(0)
	global_store_dwordx4 v[230:231], v[226:229], off
	v_mul_f32_e32 v51, 0x45800000, v50
	v_cndmask_b32_e32 v51, v50, v51, vcc
	v_mul_f32_e32 v50, 0xbfb8aa3b, v51
	v_pk_mul_f32 v[52:53], v[44:45], v[50:51] op_sel_hi:[1,0]
	v_pk_mul_f32 v[44:45], v[46:47], v[50:51] op_sel_hi:[1,0]
	v_exp_f32_e32 v52, v52
	v_exp_f32_e32 v53, v53
	v_exp_f32_e32 v44, v44
	v_exp_f32_e32 v45, v45
	v_mul_f32_e32 v48, v51, v51
	v_pk_add_f32 v[52:53], v[52:53], 1.0 op_sel_hi:[1,0]
	v_pk_add_f32 v[44:45], v[44:45], 1.0 op_sel_hi:[1,0]
	v_rcp_f32_e32 v52, v52
	v_rcp_f32_e32 v53, v53
	v_rcp_f32_e32 v44, v44
	v_rcp_f32_e32 v45, v45
	v_pk_mul_f32 v[46:47], v[48:49], v[52:53] op_sel_hi:[0,1]
	v_pk_mul_f32 v[40:41], v[40:41], v[46:47]
	v_pk_mul_f32 v[46:47], v[36:37], v[50:51] op_sel_hi:[1,0]
	v_pk_mul_f32 v[44:45], v[48:49], v[44:45] op_sel_hi:[0,1]
	v_exp_f32_e32 v46, v46
	v_exp_f32_e32 v47, v47
	v_pk_mul_f32 v[42:43], v[42:43], v[44:45]
	v_cvt_pk_bf16_f32 v40, v40, v41
	v_pk_mul_f32 v[36:37], v[38:39], v[50:51] op_sel_hi:[1,0]
	v_cvt_pk_bf16_f32 v41, v42, v43
	v_pk_add_f32 v[42:43], v[46:47], 1.0 op_sel_hi:[1,0]
	v_exp_f32_e32 v36, v36
	v_rcp_f32_e32 v42, v42
	v_rcp_f32_e32 v43, v43
	v_exp_f32_e32 v37, v37
	v_pk_mul_f32 v[38:39], v[48:49], v[42:43] op_sel_hi:[0,1]
	v_pk_mul_f32 v[32:33], v[32:33], v[38:39]
	s_nop 0
	v_cvt_pk_bf16_f32 v42, v32, v33
	v_pk_add_f32 v[32:33], v[36:37], 1.0 op_sel_hi:[1,0]
	v_ffbh_u32_e32 v36, v123
	v_min_u32_e32 v38, 32, v36
	v_lshlrev_b64 v[36:37], v38, v[122:123]
	v_rcp_f32_e32 v32, v32
	v_rcp_f32_e32 v33, v33
	v_min_u32_e32 v36, 1, v36
	v_or_b32_e32 v36, v37, v36
	v_cvt_f32_u32_e32 v36, v36
	v_pk_mul_f32 v[32:33], v[48:49], v[32:33] op_sel_hi:[0,1]
	v_pk_mul_f32 v[32:33], v[34:35], v[32:33]
	v_sub_u32_e32 v34, 32, v38
	v_ldexp_f32 v34, v36, v34
	v_mul_f32_e32 v34, 0x33800000, v34
	v_fmamk_f32 v34, v34, 0x39800000, v158
	v_mul_f32_e32 v35, 0x4b800000, v34
	v_cmp_gt_f32_e32 vcc, s57, v34
	v_cvt_pk_bf16_f32 v43, v32, v33
	v_mad_i64_i32 v[32:33], s[4:5], v160, s58, v[120:121]
	s_nop 0
	v_cndmask_b32_e32 v34, v34, v35, vcc
	v_rsq_f32_e32 v34, v34
	v_lshl_add_u64 v[32:33], v[32:33], 0, v[116:117]
	ds_bpermute_b32 v230, v232, v32
	ds_bpermute_b32 v231, v232, v33
	ds_bpermute_b32 v234, v232, v40
	ds_bpermute_b32 v235, v232, v41
	ds_bpermute_b32 v236, v232, v42
	ds_bpermute_b32 v237, v232, v43
	s_waitcnt lgkmcnt(0)
; __device__ __forceinline__ unsigned cvt_pk_bf16(float lo, float hi) { unsigned r; asm volatile("v_cvt_pk_bf16_f32 %0, %1, %2" : "=v"(r) : "v"(lo), "v"(hi)); return r; }
; #define PG8_BAR __builtin_amdgcn_s_barrier()
;     __device__ __forceinline__ void operator()(const f32x4 (&acc)[2][2][4][2], const Unit& u, int wr, int wc, int fr, int fq) const {
;     ...
;                 const int row = row0 + ai * HALF + m * 16; const float rs = rsqrtf((float)sq[ai][m] * (1.0f / FIXS) * (1.0f / (float)D) + EPS);
;                 typedef float f2 __attribute__((ext_vector_type(2)));
;                 const float c1 = -1.4426950408889634f * rs, c2 = rs * rs;
;                 u32x4 w; unsigned wq[4];
; #pragma unroll
;                 for (int q = 0; q < 4; ++q) { const f32x4 gg = acc[ai][0][m][q >> 1], uu = acc[ai][1][m][q >> 1];
;                     const f2 g = {gg[2 * (q & 1)], gg[2 * (q & 1) + 1]}, u2 = {uu[2 * (q & 1)], uu[2 * (q & 1) + 1]};
;                     const f2 t = g * c1; const f2 e = {__builtin_amdgcn_exp2f(t.x), __builtin_amdgcn_exp2f(t.y)};
;                     const f2 d = e + 1.0f; const f2 r = {__builtin_amdgcn_rcpf(d.x), __builtin_amdgcn_rcpf(d.y)};
;                     const f2 o = (g * u2) * (r * c2);
;                     wq[q] = cvt_pk_bf16(o.x, o.y); }
;                 w.x = wq[0]; w.y = wq[1]; w.z = wq[2]; w.w = wq[3];
;                 *(u32x4*)(O + (size_t)row * LDF + col0) = w;
; template <class Epi, class Sched, bool ALIGN_EPI = false, bool SP2 = false>
; __device__ __forceinline__ void gemm_phase(PG8_LAS unsigned char* lds, const Gemm g, const Sched& S, const Epi& E, int wid) {
;     ...
;         if (!has_next) break;
; #pragma unroll
;         for (int a = 0; a < 2; ++a)
; #pragma unroll
;             for (int b = 0; b < 2; ++b)
; #pragma unroll
;                 for (int m = 0; m < 4; ++m)
; #pragma unroll
;                     for (int n = 0; n < 2; ++n) acc[a][b][m][n] = (f32x4){0.f, 0.f, 0.f, 0.f};
;         cur = nxt; cA = nA; cB = nB; ++ui;
;         if constexpr (ALIGN_EPI) { if (wr == 1) PG8_BAR; }
	global_store_dwordx4 v[230:231], v[234:237], off
	v_mul_f32_e32 v35, 0x45800000, v34
	v_cndmask_b32_e32 v35, v34, v35, vcc
	v_mul_f32_e32 v34, 0xbfb8aa3b, v35
	v_pk_mul_f32 v[36:37], v[28:29], v[34:35] op_sel_hi:[1,0]
	v_pk_mul_f32 v[28:29], v[30:31], v[34:35] op_sel_hi:[1,0]
	v_exp_f32_e32 v36, v36
	v_exp_f32_e32 v37, v37
	v_exp_f32_e32 v28, v28
	v_exp_f32_e32 v29, v29
	v_mul_f32_e32 v32, v35, v35
	v_pk_add_f32 v[36:37], v[36:37], 1.0 op_sel_hi:[1,0]
	v_pk_add_f32 v[28:29], v[28:29], 1.0 op_sel_hi:[1,0]
	v_rcp_f32_e32 v36, v36
	v_rcp_f32_e32 v37, v37
	v_rcp_f32_e32 v28, v28
	v_rcp_f32_e32 v29, v29
	v_pk_mul_f32 v[30:31], v[32:33], v[36:37] op_sel_hi:[0,1]
	v_pk_mul_f32 v[24:25], v[24:25], v[30:31]
	v_pk_mul_f32 v[30:31], v[20:21], v[34:35] op_sel_hi:[1,0]
	v_pk_mul_f32 v[28:29], v[32:33], v[28:29] op_sel_hi:[0,1]
	v_exp_f32_e32 v30, v30
	v_exp_f32_e32 v31, v31
	v_pk_mul_f32 v[26:27], v[26:27], v[28:29]
	v_cvt_pk_bf16_f32 v24, v24, v25
	v_pk_mul_f32 v[20:21], v[22:23], v[34:35] op_sel_hi:[1,0]
	v_cvt_pk_bf16_f32 v25, v26, v27
	v_pk_add_f32 v[26:27], v[30:31], 1.0 op_sel_hi:[1,0]
	v_exp_f32_e32 v20, v20
	v_rcp_f32_e32 v26, v26
	v_rcp_f32_e32 v27, v27
	v_exp_f32_e32 v21, v21
	v_pk_mul_f32 v[22:23], v[32:33], v[26:27] op_sel_hi:[0,1]
	v_pk_mul_f32 v[16:17], v[16:17], v[22:23]
	s_nop 0
	v_cvt_pk_bf16_f32 v26, v16, v17
	v_pk_add_f32 v[16:17], v[20:21], 1.0 op_sel_hi:[1,0]
	v_ffbh_u32_e32 v20, v119
	v_min_u32_e32 v22, 32, v20
	v_lshlrev_b64 v[20:21], v22, v[118:119]
	v_rcp_f32_e32 v16, v16
	v_rcp_f32_e32 v17, v17
	v_min_u32_e32 v20, 1, v20
	v_or_b32_e32 v20, v21, v20
	v_cvt_f32_u32_e32 v20, v20
	v_pk_mul_f32 v[16:17], v[32:33], v[16:17] op_sel_hi:[0,1]
	v_pk_mul_f32 v[16:17], v[18:19], v[16:17]
	v_sub_u32_e32 v18, 32, v22
	v_ldexp_f32 v18, v20, v18
	v_mul_f32_e32 v18, 0x33800000, v18
	v_fmamk_f32 v18, v18, 0x39800000, v158
	v_mul_f32_e32 v19, 0x4b800000, v18
	v_cmp_gt_f32_e32 vcc, s57, v18
	v_cvt_pk_bf16_f32 v27, v16, v17
	v_mad_i64_i32 v[16:17], s[4:5], v159, s58, v[120:121]
	s_nop 0
	v_cndmask_b32_e32 v18, v18, v19, vcc
	v_rsq_f32_e32 v18, v18
	v_lshl_add_u64 v[16:17], v[16:17], 0, v[116:117]
	ds_bpermute_b32 v230, v232, v16
	ds_bpermute_b32 v231, v232, v17
	ds_bpermute_b32 v226, v232, v24
	ds_bpermute_b32 v227, v232, v25
	ds_bpermute_b32 v228, v232, v26
	ds_bpermute_b32 v229, v232, v27
	s_waitcnt lgkmcnt(0)
	global_store_dwordx4 v[230:231], v[226:229], off
	v_mul_f32_e32 v19, 0x45800000, v18
	v_cndmask_b32_e32 v19, v18, v19, vcc
	v_mul_f32_e32 v18, 0xbfb8aa3b, v19
	v_pk_mul_f32 v[20:21], v[12:13], v[18:19] op_sel_hi:[1,0]
	v_pk_mul_f32 v[12:13], v[14:15], v[18:19] op_sel_hi:[1,0]
	v_exp_f32_e32 v20, v20
	v_exp_f32_e32 v21, v21
	v_exp_f32_e32 v12, v12
	v_exp_f32_e32 v13, v13
	v_mul_f32_e32 v16, v19, v19
	v_pk_add_f32 v[20:21], v[20:21], 1.0 op_sel_hi:[1,0]
	s_and_b64 vcc, exec, s[2:3]
	v_rcp_f32_e32 v20, v20
	v_rcp_f32_e32 v21, v21
	v_pk_add_f32 v[12:13], v[12:13], 1.0 op_sel_hi:[1,0]
	s_mov_b64 s[2:3], -1
	v_rcp_f32_e32 v12, v12
	v_rcp_f32_e32 v13, v13
	v_pk_mul_f32 v[14:15], v[16:17], v[20:21] op_sel_hi:[0,1]
	v_pk_mul_f32 v[8:9], v[8:9], v[14:15]
	v_pk_mul_f32 v[14:15], v[4:5], v[18:19] op_sel_hi:[1,0]
	v_pk_mul_f32 v[12:13], v[16:17], v[12:13] op_sel_hi:[0,1]
	v_exp_f32_e32 v14, v14
	v_exp_f32_e32 v15, v15
	v_pk_mul_f32 v[10:11], v[10:11], v[12:13]
	v_pk_mul_f32 v[12:13], v[6:7], v[18:19] op_sel_hi:[1,0]
	v_cvt_pk_bf16_f32 v8, v8, v9
	v_cvt_pk_bf16_f32 v9, v10, v11
	v_pk_add_f32 v[10:11], v[14:15], 1.0 op_sel_hi:[1,0]
	v_exp_f32_e32 v12, v12
	v_exp_f32_e32 v13, v13
	v_rcp_f32_e32 v10, v10
	v_rcp_f32_e32 v11, v11
	v_pk_add_f32 v[4:5], v[12:13], 1.0 op_sel_hi:[1,0]
	s_nop 0
	v_rcp_f32_e32 v4, v4
	v_rcp_f32_e32 v5, v5
	v_pk_mul_f32 v[6:7], v[16:17], v[10:11] op_sel_hi:[0,1]
	v_pk_mul_f32 v[0:1], v[0:1], v[6:7]
	s_nop 0
	v_cvt_pk_bf16_f32 v10, v0, v1
	v_pk_mul_f32 v[0:1], v[16:17], v[4:5] op_sel_hi:[0,1]
	v_pk_mul_f32 v[0:1], v[2:3], v[0:1]
	s_nop 0
	v_cvt_pk_bf16_f32 v11, v0, v1
	v_mad_i64_i32 v[0:1], s[4:5], v147, s58, v[120:121]
	v_lshl_add_u64 v[0:1], v[0:1], 0, v[116:117]
	ds_bpermute_b32 v230, v232, v0
	ds_bpermute_b32 v231, v232, v1
	ds_bpermute_b32 v234, v232, v8
	ds_bpermute_b32 v235, v232, v9
	ds_bpermute_b32 v236, v232, v10
	ds_bpermute_b32 v237, v232, v11
	s_waitcnt lgkmcnt(0)
	global_store_dwordx4 v[230:231], v[234:237], off
	s_cbranch_vccnz .LBB0_1125
	s_andn2_b64 vcc, exec, s[6:7]
	s_cbranch_vccnz .LBB0_1124
	s_barrier
	s_branch .LBB0_1124
